# speedup vs baseline: 1.0030x; 1.0015x over previous
; template <bool BOUNDARY, bool Q0, bool Q1>
; __device__ __forceinline__ void attn_tile(const bf16* Ks, const bf16* Vt, const bf16x8 (&Qf)[2][2], const uint32_t (&vm)[2],
;                                           float (&m)[2], float (&l)[2], f32x4 (&O)[4][2], int fr, int fq) {
;   f32x4 S[4][2];
; #pragma unroll
;   for (int kt = 0; kt < 4; ++kt) {
;     S[kt][0] = f32x4{0.f, 0.f, 0.f, 0.f};
;     S[kt][1] = f32x4{0.f, 0.f, 0.f, 0.f};
; #pragma unroll
;     for (int ks = 0; ks < 2; ++ks) {
;       const bf16x8 kf = *(const bf16x8*)(Ks + (16 * kt + fr) * KS_LD + 32 * ks + 8 * fq);
;       if (Q0) S[kt][0] = __builtin_amdgcn_mfma_f32_16x16x32_bf16(kf, Qf[0][ks], S[kt][0], 0, 0, 0);
;       if (Q1) S[kt][1] = __builtin_amdgcn_mfma_f32_16x16x32_bf16(kf, Qf[1][ks], S[kt][1], 0, 0, 0);
;     }
;   }
; #pragma unroll
;   for (int qt = 0; qt < 2; ++qt) {
;     if ((qt == 0 && !Q0) || (qt == 1 && !Q1)) continue;
;     float mx, mxu;
;     if (BOUNDARY) {
;       mx = m[qt];
; #pragma unroll
;       for (int kt = 0; kt < 4; ++kt)
; #pragma unroll
;         for (int j = 0; j < 4; ++j) {
;           const float s2 = S[kt][qt][j];
;           if ((vm[qt] >> (kt * 4 + j)) & 1u) mx = fmaxf(mx, s2);
;         }
;       mx = fmaxf(mx, __shfl_xor(mx, 16));
;       mx = fmaxf(mx, __shfl_xor(mx, 32));
;       mxu = mx;
;     } else {
;       float rm = -3.0e38f;
; #pragma unroll
;       for (int kt = 0; kt < 4; ++kt)
; #pragma unroll
;         for (int j = 0; j < 4; ++j) {
;           rm = fmaxf(rm, S[kt][qt][j]);
;         }
;       rm = fmaxf(rm, __shfl_xor(rm, 16));
;       rm = fmaxf(rm, __shfl_xor(rm, 32));
;       const bool rv = vm[qt] != 0u;
;       mx = rv ? fmaxf(m[qt], rm) : m[qt];
;       mxu = rv ? mx : 3.0e38f;
;     }
;     const float alpha = __builtin_amdgcn_exp2f(m[qt] - mx);
;     m[qt] = mx;
;     float ls = 0.f;
; #pragma unroll
;     for (int kt = 0; kt < 4; ++kt)
; #pragma unroll
;       for (int j = 0; j < 4; ++j) {
;         float pv;
;         if (BOUNDARY) pv = ((vm[qt] >> (kt * 4 + j)) & 1u) ? __builtin_amdgcn_exp2f(S[kt][qt][j] - mxu) : 0.f;
;         else pv = __builtin_amdgcn_exp2f(S[kt][qt][j] - mxu);
;         S[kt][qt][j] = pv;
;         ls += pv;
;       }
;     l[qt] = l[qt] * alpha + ls;
; #pragma unroll
;     for (int dt = 0; dt < 4; ++dt) {
.Lslc_mask_done:
	v_cmp_ne_u32_e64 s[6:7], 0, v142
	v_mul_lo_u32 v138, v135, s40
	v_cmp_ne_u32_e32 vcc, s62, v134
	v_cndmask_b32_e64 v146, 0, 1, s[6:7]
	v_cmp_ne_u32_e64 s[6:7], 0, v140
	s_nop 1
	v_cndmask_b32_e64 v145, 0, 1, s[6:7]
	s_and_saveexec_b64 s[6:7], vcc
	s_xor_b64 s[6:7], exec, s[6:7]
	s_cbranch_execz .LBB0_656
	v_cmp_ne_u32_e64 s[8:9], 0, v142
	v_cmp_ne_u32_e64 s[10:11], 0, v140
	s_cmp_eq_u64 s[8:9], 0
	s_cselect_b64 s[12:13], -1, 0
	s_cmp_lg_u64 s[8:9], 0
	s_cselect_b64 s[8:9], -1, 0
	s_cmp_lg_u64 s[10:11], 0
	s_cselect_b64 s[10:11], -1, 0
	s_and_b64 s[8:9], s[8:9], s[10:11]
	s_andn2_b64 vcc, exec, s[8:9]
	s_mov_b64 s[8:9], -1
	s_cbranch_vccz .LBB0_665
	s_and_b64 vcc, exec, s[12:13]
	s_cbranch_vccz .LBB0_662
	s_andn2_b64 vcc, exec, s[10:11]
	s_cbranch_vccnz .LBB0_661
	v_add_u32_e32 v100, v138, v152
	v_add_u32_e32 v96, v100, v230
	ds_read_b128 v[92:95], v96
	v_add_u32_e32 v108, v100, v163
	ds_read_b128 v[100:103], v108 offset:64
	ds_read_b128 v[96:99], v96 offset:64
	ds_read_b128 v[104:107], v108 offset:2368
	v_cmp_eq_u32_e32 vcc, 0, v140
	s_mov_b64 s[8:9], 0
	s_waitcnt lgkmcnt(3)
	v_mfma_f32_16x16x32_bf16 v[92:95], v[92:95], v[8:11], 0
	s_waitcnt lgkmcnt(1)
	v_mfma_f32_16x16x32_bf16 v[92:95], v[96:99], v[12:15], v[92:95]
	ds_read_b128 v[96:99], v108
	s_waitcnt lgkmcnt(0)
	v_mfma_f32_16x16x32_bf16 v[96:99], v[96:99], v[8:11], 0
	v_mfma_f32_16x16x32_bf16 v[96:99], v[100:103], v[12:15], v[96:99]
	ds_read_b128 v[100:103], v108 offset:2304
	s_waitcnt lgkmcnt(0)
	v_mfma_f32_16x16x32_bf16 v[100:103], v[100:103], v[8:11], 0
	v_mfma_f32_16x16x32_bf16 v[100:103], v[104:107], v[12:15], v[100:103]
	ds_read_b128 v[104:107], v108 offset:4608
	ds_read_b128 v[108:111], v108 offset:4672
	s_waitcnt lgkmcnt(1)
	v_mfma_f32_16x16x32_bf16 v[104:107], v[104:107], v[8:11], 0
	s_waitcnt lgkmcnt(0)
	v_mfma_f32_16x16x32_bf16 v[104:107], v[108:111], v[12:15], v[104:107]
	v_max3_f32 v108, v92, s49, v93
	v_max3_f32 v108, v108, v94, v95
	v_max3_f32 v108, v108, v96, v97
	v_max3_f32 v108, v108, v98, v99
	v_max3_f32 v108, v108, v100, v101
	v_max3_f32 v108, v108, v102, v103
	s_nop 1
	v_max3_f32 v108, v108, v104, v105
	v_max3_f32 v108, v108, v106, v107
	v_mov_b32_e32 v109, v108
	s_nop 1
	v_permlane32_swap_b32_e32 v108, v109
	v_max_f32_e32 v108, v108, v109
	v_mov_b32_e32 v109, v108
	s_nop 1
	v_permlane16_swap_b32_e32 v108, v109
	v_max_f32_e32 v108, v108, v109
	v_max_f32_e32 v108, v139, v108
	v_cndmask_b32_e32 v109, v108, v215, vcc
	v_sub_f32_e32 v93, v93, v109
	v_exp_f32_e32 v111, v93
	v_sub_f32_e32 v93, v94, v109
	v_sub_f32_e32 v92, v92, v109
	v_exp_f32_e32 v112, v93
	v_sub_f32_e32 v93, v95, v109
	v_exp_f32_e32 v110, v92
	v_exp_f32_e32 v113, v93
	v_sub_f32_e32 v93, v96, v109
	v_exp_f32_e32 v114, v93
	v_sub_f32_e32 v93, v97, v109
	v_exp_f32_e32 v115, v93
	v_sub_f32_e32 v93, v98, v109
	v_exp_f32_e32 v116, v93
	v_sub_f32_e32 v93, v99, v109
	v_add_f32_e32 v92, 0, v110
	v_exp_f32_e32 v117, v93
	v_sub_f32_e32 v93, v100, v109
	v_add_f32_e32 v92, v111, v92
	v_exp_f32_e32 v118, v93
	v_sub_f32_e32 v93, v101, v109
	v_add_f32_e32 v92, v112, v92
	v_exp_f32_e32 v119, v93
	v_sub_f32_e32 v93, v102, v109
	v_add_f32_e32 v92, v113, v92
	v_exp_f32_e32 v120, v93
	v_sub_f32_e32 v93, v103, v109
	v_cndmask_b32_e32 v144, v108, v139, vcc
	v_add_f32_e32 v92, v114, v92
	v_exp_f32_e32 v121, v93
	v_sub_f32_e32 v93, v104, v109
	v_sub_f32_e32 v108, v139, v144
	v_add_f32_e32 v92, v115, v92
	v_exp_f32_e32 v122, v93
	v_sub_f32_e32 v93, v105, v109
	v_add_f32_e32 v92, v116, v92
	v_exp_f32_e32 v123, v93
	v_sub_f32_e32 v93, v106, v109
	v_exp_f32_e32 v104, v108
	v_cvt_pk_bf16_f32 v108, v110, v111
	v_cvt_pk_bf16_f32 v111, v116, v117
	v_lshlrev_b32_e32 v116, 1, v223
	v_exp_f32_e32 v143, v93
	v_sub_f32_e32 v93, v107, v109
	v_cvt_pk_bf16_f32 v109, v112, v113
	v_add3_u32 v112, v138, v231, v116
	v_add_f32_e32 v92, v117, v92
	v_add_u32_e32 v117, 0x2000, v112
	v_cvt_pk_bf16_f32 v110, v114, v115
	ds_read2_b64 v[112:115], v117 offset0:128 offset1:132
	v_add_f32_e32 v92, v118, v92
	v_add_f32_e32 v92, v119, v92
	v_add_f32_e32 v92, v120, v92
	v_add_f32_e32 v92, v121, v92
	v_exp_f32_e32 v145, v93
	v_add_f32_e32 v92, v122, v92
	v_add_f32_e32 v92, v123, v92
	v_add_f32_e32 v92, v143, v92
	v_add_f32_e32 v146, v145, v92
	v_pk_mul_f32 v[94:95], v[74:75], v[104:105] op_sel_hi:[1,0]
	v_pk_mul_f32 v[92:93], v[72:73], v[104:105] op_sel_hi:[1,0]
	v_pk_mul_f32 v[98:99], v[70:71], v[104:105] op_sel_hi:[1,0]
	v_pk_mul_f32 v[96:97], v[68:69], v[104:105] op_sel_hi:[1,0]
	s_waitcnt lgkmcnt(0)
	v_mfma_f32_16x16x32_bf16 v[92:95], v[112:115], v[108:111], v[92:95]
	v_lshlrev_b32_e32 v112, 1, v233
	v_add3_u32 v116, v138, v112, v116
	v_add_u32_e32 v147, 0x2000, v116
	ds_read2_b64 v[112:115], v147 offset0:128 offset1:132
	v_add_u32_e32 v148, 0x2800, v116
	s_waitcnt lgkmcnt(0)
	v_mfma_f32_16x16x32_bf16 v[96:99], v[112:115], v[108:111], v[96:99]
	ds_read2_b64 v[112:115], v148 offset0:144 offset1:148
	v_pk_mul_f32 v[102:103], v[66:67], v[104:105] op_sel_hi:[1,0]
	v_pk_mul_f32 v[100:101], v[64:65], v[104:105] op_sel_hi:[1,0]
	v_add_u32_e32 v116, 0x3000, v116
	v_fmac_f32_e32 v146, v133, v104
	s_waitcnt lgkmcnt(0)
	v_mfma_f32_16x16x32_bf16 v[100:103], v[112:115], v[108:111], v[100:103]
	ds_read2_b64 v[112:115], v116 offset0:160 offset1:164
	v_pk_mul_f32 v[106:107], v[62:63], v[104:105] op_sel_hi:[1,0]
	v_pk_mul_f32 v[104:105], v[60:61], v[104:105] op_sel_hi:[1,0]
	s_waitcnt lgkmcnt(0)
	s_nop 0
	v_mfma_f32_16x16x32_bf16 v[108:111], v[112:115], v[108:111], v[104:107]
	s_nop 2
	ds_read2_b64 v[104:107], v117 offset0:136 offset1:140
	v_cvt_pk_bf16_f32 v112, v118, v119
	v_cvt_pk_bf16_f32 v113, v120, v121
	v_cvt_pk_bf16_f32 v114, v122, v123
	v_cvt_pk_bf16_f32 v115, v143, v145
	v_mov_b32_e32 v143, v141
	s_waitcnt lgkmcnt(0)
	v_mfma_f32_16x16x32_bf16 v[92:95], v[104:107], v[112:115], v[92:95]
	ds_read2_b64 v[104:107], v147 offset0:136 offset1:140
	s_waitcnt lgkmcnt(0)
	v_mfma_f32_16x16x32_bf16 v[96:99], v[104:107], v[112:115], v[96:99]
	ds_read2_b64 v[104:107], v148 offset0:152 offset1:156
	s_waitcnt lgkmcnt(0)
	v_mfma_f32_16x16x32_bf16 v[104:107], v[104:107], v[112:115], v[100:103]
	s_nop 2
	ds_read2_b64 v[100:103], v116 offset0:168 offset1:172
	s_waitcnt lgkmcnt(0)
	v_mfma_f32_16x16x32_bf16 v[116:119], v[100:103], v[112:115], v[108:111]
	s_branch .LBB0_662

; template <bool BOUNDARY, bool Q0, bool Q1>
; __device__ __forceinline__ void attn_tile(const bf16* Ks, const bf16* Vt, const bf16x8 (&Qf)[2][2], const uint32_t (&vm)[2],
;                                           float (&m)[2], float (&l)[2], f32x4 (&O)[4][2], int fr, int fq) {
;   f32x4 S[4][2];
; #pragma unroll
;   for (int kt = 0; kt < 4; ++kt) {
;     S[kt][0] = f32x4{0.f, 0.f, 0.f, 0.f};
;     S[kt][1] = f32x4{0.f, 0.f, 0.f, 0.f};
; #pragma unroll
;     for (int ks = 0; ks < 2; ++ks) {
;       const bf16x8 kf = *(const bf16x8*)(Ks + (16 * kt + fr) * KS_LD + 32 * ks + 8 * fq);
;       if (Q0) S[kt][0] = __builtin_amdgcn_mfma_f32_16x16x32_bf16(kf, Qf[0][ks], S[kt][0], 0, 0, 0);
;       if (Q1) S[kt][1] = __builtin_amdgcn_mfma_f32_16x16x32_bf16(kf, Qf[1][ks], S[kt][1], 0, 0, 0);
;     }
;   }
; #pragma unroll
;   for (int qt = 0; qt < 2; ++qt) {
;     if ((qt == 0 && !Q0) || (qt == 1 && !Q1)) continue;
;     float mx, mxu;
;     if (BOUNDARY) {
;       mx = m[qt];
; #pragma unroll
;       for (int kt = 0; kt < 4; ++kt)
; #pragma unroll
;         for (int j = 0; j < 4; ++j) {
;           const float s2 = S[kt][qt][j];
;           if ((vm[qt] >> (kt * 4 + j)) & 1u) mx = fmaxf(mx, s2);
;         }
;       mx = fmaxf(mx, __shfl_xor(mx, 16));
;       mx = fmaxf(mx, __shfl_xor(mx, 32));
;       mxu = mx;
;     } else {
;       float rm = -3.0e38f;
; #pragma unroll
;       for (int kt = 0; kt < 4; ++kt)
; #pragma unroll
;         for (int j = 0; j < 4; ++j) {
;           rm = fmaxf(rm, S[kt][qt][j]);
;         }
;       rm = fmaxf(rm, __shfl_xor(rm, 16));
;       rm = fmaxf(rm, __shfl_xor(rm, 32));
;       const bool rv = vm[qt] != 0u;
;       mx = rv ? fmaxf(m[qt], rm) : m[qt];
;       mxu = rv ? mx : 3.0e38f;
;     }
;     const float alpha = __builtin_amdgcn_exp2f(m[qt] - mx);
;     m[qt] = mx;
;     float ls = 0.f;
; #pragma unroll
;     for (int kt = 0; kt < 4; ++kt)
; #pragma unroll
;       for (int j = 0; j < 4; ++j) {
;         float pv;
;         if (BOUNDARY) pv = ((vm[qt] >> (kt * 4 + j)) & 1u) ? __builtin_amdgcn_exp2f(S[kt][qt][j] - mxu) : 0.f;
;         else pv = __builtin_amdgcn_exp2f(S[kt][qt][j] - mxu);
;         S[kt][qt][j] = pv;
;         ls += pv;
;       }
;     l[qt] = l[qt] * alpha + ls;
; #pragma unroll
;     for (int dt = 0; dt < 4; ++dt) {
.LBB0_662:
	v_mov_b64_e32 v[102:103], v[90:91]
	s_nop 0
	v_mov_b64_e32 v[110:111], v[86:87]
	v_mov_b64_e32 v[114:115], v[82:83]
	v_mov_b64_e32 v[122:123], v[78:79]
	s_andn2_b64 vcc, exec, s[8:9]
	v_mov_b32_e32 v145, v132
	v_mov_b64_e32 v[100:101], v[88:89]
	v_mov_b64_e32 v[108:109], v[84:85]
	v_mov_b64_e32 v[112:113], v[80:81]
	v_mov_b64_e32 v[120:121], v[76:77]
	s_cbranch_vccnz .LBB0_664
	v_add_u32_e32 v100, v138, v152
	v_add_u32_e32 v96, v100, v230
	ds_read_b128 v[92:95], v96
	v_add_u32_e32 v108, v100, v163
	ds_read_b128 v[100:103], v108 offset:64
	ds_read_b128 v[96:99], v96 offset:64
	ds_read_b128 v[104:107], v108 offset:2368
	v_cmp_eq_u32_e32 vcc, 0, v142
	s_waitcnt lgkmcnt(3)
	v_mfma_f32_16x16x32_bf16 v[92:95], v[92:95], v[0:3], 0
	s_waitcnt lgkmcnt(1)
	v_mfma_f32_16x16x32_bf16 v[92:95], v[96:99], v[4:7], v[92:95]
	ds_read_b128 v[96:99], v108
	s_waitcnt lgkmcnt(0)
	v_mfma_f32_16x16x32_bf16 v[96:99], v[96:99], v[0:3], 0
	v_mfma_f32_16x16x32_bf16 v[96:99], v[100:103], v[4:7], v[96:99]
	ds_read_b128 v[100:103], v108 offset:2304
	s_waitcnt lgkmcnt(0)
	v_mfma_f32_16x16x32_bf16 v[100:103], v[100:103], v[0:3], 0
	v_mfma_f32_16x16x32_bf16 v[100:103], v[104:107], v[4:7], v[100:103]
	ds_read_b128 v[104:107], v108 offset:4608
	ds_read_b128 v[108:111], v108 offset:4672
	s_waitcnt lgkmcnt(1)
	v_mfma_f32_16x16x32_bf16 v[104:107], v[104:107], v[0:3], 0
	s_waitcnt lgkmcnt(0)
	v_mfma_f32_16x16x32_bf16 v[104:107], v[108:111], v[4:7], v[104:107]
	v_max3_f32 v108, v92, s49, v93
	v_max3_f32 v108, v108, v94, v95
	v_max3_f32 v108, v108, v96, v97
	v_max3_f32 v108, v108, v98, v99
	v_max3_f32 v108, v108, v100, v101
	v_max3_f32 v108, v108, v102, v103
	s_nop 1
	v_max3_f32 v108, v108, v104, v105
	v_max3_f32 v108, v108, v106, v107
	v_mov_b32_e32 v109, v108
	s_nop 1
	v_permlane32_swap_b32_e32 v108, v109
	v_max_f32_e32 v108, v108, v109
	v_mov_b32_e32 v109, v108
	s_nop 1
	v_permlane16_swap_b32_e32 v108, v109
	v_max_f32_e32 v108, v108, v109
	v_max_f32_e32 v108, v141, v108
	v_cndmask_b32_e32 v109, v108, v215, vcc
	v_sub_f32_e32 v93, v93, v109
	v_exp_f32_e32 v111, v93
	v_sub_f32_e32 v93, v94, v109
	v_sub_f32_e32 v92, v92, v109
	v_exp_f32_e32 v112, v93
	v_sub_f32_e32 v93, v95, v109
	v_exp_f32_e32 v110, v92
	v_exp_f32_e32 v113, v93
	v_sub_f32_e32 v93, v96, v109
	v_exp_f32_e32 v114, v93
	v_sub_f32_e32 v93, v97, v109
	v_exp_f32_e32 v115, v93
	v_sub_f32_e32 v93, v98, v109
	v_exp_f32_e32 v116, v93
	v_sub_f32_e32 v93, v99, v109
	v_add_f32_e32 v92, 0, v110
	v_exp_f32_e32 v117, v93
	v_sub_f32_e32 v93, v100, v109
	v_add_f32_e32 v92, v111, v92
	v_exp_f32_e32 v118, v93
	v_sub_f32_e32 v93, v101, v109
	v_add_f32_e32 v92, v112, v92
	v_exp_f32_e32 v119, v93
	v_sub_f32_e32 v93, v102, v109
	v_add_f32_e32 v92, v113, v92
	v_exp_f32_e32 v120, v93
	v_sub_f32_e32 v93, v103, v109
	v_cndmask_b32_e32 v143, v108, v141, vcc
	v_add_f32_e32 v92, v114, v92
	v_exp_f32_e32 v121, v93
	v_sub_f32_e32 v93, v104, v109
	v_sub_f32_e32 v108, v141, v143
	v_add_f32_e32 v92, v115, v92
	v_exp_f32_e32 v122, v93
	v_sub_f32_e32 v93, v105, v109
	v_add_f32_e32 v92, v116, v92
	v_exp_f32_e32 v123, v93
	v_sub_f32_e32 v93, v106, v109
	v_exp_f32_e32 v104, v108
	v_cvt_pk_bf16_f32 v108, v110, v111
	v_cvt_pk_bf16_f32 v111, v116, v117
	v_lshlrev_b32_e32 v116, 1, v223
	v_exp_f32_e32 v144, v93
	v_sub_f32_e32 v93, v107, v109
	v_cvt_pk_bf16_f32 v109, v112, v113
	v_add3_u32 v112, v138, v231, v116
	v_add_u32_e32 v147, 0x2000, v112
	v_add_f32_e32 v92, v117, v92
	v_cvt_pk_bf16_f32 v110, v114, v115
	ds_read2_b64 v[112:115], v147 offset0:128 offset1:132
	v_add_f32_e32 v92, v118, v92
	v_add_f32_e32 v92, v119, v92
	v_add_f32_e32 v92, v120, v92
	v_add_f32_e32 v92, v121, v92
	v_exp_f32_e32 v146, v93
	v_add_f32_e32 v92, v122, v92
	v_add_f32_e32 v92, v123, v92
	v_add_f32_e32 v92, v144, v92
	v_add_f32_e32 v145, v146, v92
	v_pk_mul_f32 v[94:95], v[90:91], v[104:105] op_sel_hi:[1,0]
	v_pk_mul_f32 v[92:93], v[88:89], v[104:105] op_sel_hi:[1,0]
	v_pk_mul_f32 v[98:99], v[86:87], v[104:105] op_sel_hi:[1,0]
	v_pk_mul_f32 v[96:97], v[84:85], v[104:105] op_sel_hi:[1,0]
	s_waitcnt lgkmcnt(0)
	v_mfma_f32_16x16x32_bf16 v[92:95], v[112:115], v[108:111], v[92:95]
	v_lshlrev_b32_e32 v112, 1, v233
	v_add3_u32 v116, v138, v112, v116
	v_add_u32_e32 v148, 0x2000, v116
	ds_read2_b64 v[112:115], v148 offset0:128 offset1:132
	v_add_u32_e32 v149, 0x2800, v116
	s_waitcnt lgkmcnt(0)
	v_mfma_f32_16x16x32_bf16 v[96:99], v[112:115], v[108:111], v[96:99]
	ds_read2_b64 v[112:115], v149 offset0:144 offset1:148
	v_pk_mul_f32 v[102:103], v[82:83], v[104:105] op_sel_hi:[1,0]
	v_pk_mul_f32 v[100:101], v[80:81], v[104:105] op_sel_hi:[1,0]
	v_add_u32_e32 v150, 0x3000, v116
	v_fmac_f32_e32 v145, v132, v104
	s_waitcnt lgkmcnt(0)
	v_mfma_f32_16x16x32_bf16 v[112:115], v[112:115], v[108:111], v[100:103]
	s_nop 2
	ds_read2_b64 v[100:103], v150 offset0:160 offset1:164
	v_pk_mul_f32 v[106:107], v[78:79], v[104:105] op_sel_hi:[1,0]
	v_pk_mul_f32 v[104:105], v[76:77], v[104:105] op_sel_hi:[1,0]
	v_cvt_pk_bf16_f32 v116, v118, v119
	v_cvt_pk_bf16_f32 v117, v120, v121
	s_waitcnt lgkmcnt(0)
	v_mfma_f32_16x16x32_bf16 v[104:107], v[100:103], v[108:111], v[104:107]
	ds_read2_b64 v[100:103], v147 offset0:136 offset1:140
	v_cvt_pk_bf16_f32 v118, v122, v123
	v_cvt_pk_bf16_f32 v119, v144, v146
	v_mov_b32_e32 v144, v139
	v_mov_b32_e32 v146, v133
	s_waitcnt lgkmcnt(0)
	v_mfma_f32_16x16x32_bf16 v[100:103], v[100:103], v[116:119], v[92:95]
	s_nop 2
	ds_read2_b64 v[92:95], v148 offset0:136 offset1:140
	s_waitcnt lgkmcnt(0)
	v_mfma_f32_16x16x32_bf16 v[108:111], v[92:95], v[116:119], v[96:99]
	ds_read2_b64 v[92:95], v149 offset0:152 offset1:156
	s_nop 1
	v_mov_b64_e32 v[98:99], v[70:71]
	v_mov_b64_e32 v[96:97], v[68:69]
	s_waitcnt lgkmcnt(0)
	v_mfma_f32_16x16x32_bf16 v[112:115], v[92:95], v[116:119], v[112:115]
	ds_read2_b64 v[92:95], v150 offset0:168 offset1:172
	s_waitcnt lgkmcnt(0)
	v_mfma_f32_16x16x32_bf16 v[120:123], v[92:95], v[116:119], v[104:107]
	v_mov_b64_e32 v[94:95], v[74:75]
	s_nop 1
	v_mov_b64_e32 v[106:107], v[66:67]
	v_mov_b64_e32 v[118:119], v[62:63]
	v_mov_b64_e32 v[92:93], v[72:73]
	v_mov_b64_e32 v[104:105], v[64:65]
	v_mov_b64_e32 v[116:117], v[60:61]
